# sa3 + DMA blocks trimmed: second V piece reuses m0 (+0x2000), m0 computed before the address adds so no s_nop is needed
# speedup vs baseline: 1.0081x; 1.0033x over previous
; #define TWAIT_BAR(N) asm volatile("s_waitcnt vmcnt(" #N ") lgkmcnt(0)\n\ts_barrier" ::: "memory")
; #define RESC() do { if constexpr (!NOMAX) if (resc) { asm volatile("s_waitcnt lgkmcnt(0)" ::: "memory"); \
;         _Pragma("unroll") for (int d_ = 0; d_ < 2; ++d_) _Pragma("unroll") for (int r = 0; r < 16; ++r) o[d_][r] *= wsf[crow(r, hi)]; } } while (0)
; #define ROT() do { sl_prev = sl_cur; sl_cur = sl_next; sl_next = (sl_next == 2 * SLOTB) ? 0 : sl_next + SLOTB; } while (0)
; #define RESC() do { if constexpr (!NOMAX) if (resc) { asm volatile("s_waitcnt lgkmcnt(0)" ::: "memory"); \
;         _Pragma("unroll") for (int d_ = 0; d_ < 4; ++d_) _Pragma("unroll") for (int r = 0; r < 16; ++r) o[d_][r] *= wsf[crow(r, hi)]; } } while (0)
; #define ROT() do { sl_prev = sl_cur; sl_cur = sl_next; sl_next = (sl_next == 2) ? 0 : sl_next + 1; } while (0)
; #define RESC() do { if (resc) { asm volatile("s_waitcnt lgkmcnt(0)" ::: "memory"); \
;         _Pragma("unroll") for (int d_ = 0; d_ < 4; ++d_) _Pragma("unroll") for (int r = 0; r < 16; ++r) o[d_][r] *= wsf[crow(r, hi)]; } } while (0)
; template <bool NOMAX>
; __device__ __forceinline__ void diff_unit(const AttnCtx& C, int u, LAS unsigned char* lds) {
;     ...
;     int kk = 1;
;     for (; kk + 7 < n; kk += 2) {
;         STEP(pB0, pB1, pA0, pA1, kk, true, true, true, false);     TWAIT_BAR(3); RESC(); ROT();
.LBB0_463:
	s_mov_b32 s8, s60
	s_mov_b32 s9, s16
	s_mov_b32 s10, s59
	ds_read_b128 v[4:7], v219 offset:1024
	v_lshl_add_u32 v207, s11, 14, v214
	v_add_f32_e32 v2, v100, v101
	v_add_f32_e32 v2, v102, v2
	v_add_f32_e32 v2, v103, v2
	v_add_f32_e32 v2, v104, v2
	v_add_f32_e32 v2, v105, v2
	v_cvt_pk_bf16_f32 v160, v100, v101
	v_cvt_pk_bf16_f32 v161, v102, v103
	s_waitcnt lgkmcnt(1)
	v_mfma_f32_32x32x16_bf16 v[132:147], v[192:195], v[116:119], 0
	v_mfma_f32_32x32x16_bf16 v[116:131], v[184:187], v[116:119], 0
	v_add_f32_e32 v2, v106, v2
	v_add_f32_e32 v2, v107, v2
	v_add_f32_e32 v2, v108, v2
	v_add_f32_e32 v2, v109, v2
	v_cvt_pk_bf16_f32 v162, v104, v105
	v_cvt_pk_bf16_f32 v163, v106, v107
	ds_read_b128 v[10:13], v219 offset:2048
	ds_read_b64_tr_b16 v[14:15], v207 offset:24576
	ds_read_b64_tr_b16 v[16:17], v207 offset:25088
	v_add_f32_e32 v2, v110, v2
	v_add_f32_e32 v2, v111, v2
	v_add_f32_e32 v2, v112, v2
	v_add_f32_e32 v2, v113, v2
	v_cvt_pk_bf16_f32 v156, v108, v109
	v_cvt_pk_bf16_f32 v157, v110, v111
	s_waitcnt lgkmcnt(3)
	v_mfma_f32_32x32x16_bf16 v[132:147], v[188:191], v[4:7], v[132:147]
	v_mfma_f32_32x32x16_bf16 v[116:131], v[180:183], v[4:7], v[116:131]
	v_add_f32_e32 v2, v114, v2
	v_add_f32_e32 v2, v115, v2
	v_add_f32_e32 v2, v84, v2
	v_add_f32_e32 v2, v85, v2
	v_cvt_pk_bf16_f32 v158, v112, v113
	v_cvt_pk_bf16_f32 v159, v114, v115
	ds_read_b128 v[4:7], v219 offset:3072
	ds_read_b64_tr_b16 v[100:101], v207 offset:28672
	ds_read_b64_tr_b16 v[102:103], v207 offset:29184
	v_add_f32_e32 v2, v86, v2
	v_add_f32_e32 v2, v87, v2
	v_add_f32_e32 v2, v88, v2
	v_add_f32_e32 v2, v89, v2
	v_cvt_pk_bf16_f32 v152, v84, v85
	v_cvt_pk_bf16_f32 v153, v86, v87
	s_waitcnt lgkmcnt(5)
	v_mfma_f32_32x32x16_bf16 v[132:147], v[176:179], v[10:13], v[132:147]
	v_mfma_f32_32x32x16_bf16 v[116:131], v[172:175], v[10:13], v[116:131]
	v_add_f32_e32 v2, v90, v2
	v_add_f32_e32 v2, v91, v2
	v_add_f32_e32 v2, v92, v2
	v_add_f32_e32 v2, v93, v2
	v_cvt_pk_bf16_f32 v154, v88, v89
	v_cvt_pk_bf16_f32 v155, v90, v91
	ds_read_b64_tr_b16 v[84:85], v207 offset:25600
	ds_read_b64_tr_b16 v[86:87], v207 offset:26112
	v_add_f32_e32 v2, v94, v2
	v_add_f32_e32 v2, v95, v2
	v_add_f32_e32 v2, v96, v2
	v_add_f32_e32 v2, v97, v2
	v_cvt_pk_bf16_f32 v148, v92, v93
	v_cvt_pk_bf16_f32 v149, v94, v95
	s_waitcnt lgkmcnt(4)
	v_mfma_f32_32x32x16_bf16 v[132:147], v[168:171], v[4:7], v[132:147]
	v_mfma_f32_32x32x16_bf16 v[116:131], v[164:167], v[4:7], v[116:131]
	v_add_f32_e32 v2, v98, v2
	v_add_f32_e32 v2, v99, v2
	v_cvt_pk_bf16_f32 v150, v96, v97
	v_cvt_pk_bf16_f32 v151, v98, v99
	v_add_f32_e32 v2, v225, v2
	ds_read_b64_tr_b16 v[4:5], v207 offset:29696
	ds_read_b64_tr_b16 v[6:7], v207 offset:30208
	v_mfma_f32_32x32x16_bf16 v[68:83], v[160:163], v[14:17], v[68:83]
	v_exp_f32_e32 v132, v132
	v_exp_f32_e32 v133, v133
	ds_read_b64_tr_b16 v[14:15], v207 offset:26624
	ds_read_b64_tr_b16 v[16:17], v207 offset:27136
	s_waitcnt lgkmcnt(6)
	v_mfma_f32_32x32x16_bf16 v[52:67], v[160:163], v[100:103], v[52:67]
	v_exp_f32_e32 v134, v134
	v_exp_f32_e32 v135, v135
	s_lshl_b32 m0, s59, 13
	s_add_i32 m0, m0, s49
	s_add_u32 s98, s100, s28
	s_addc_u32 s99, s101, s29
	global_load_lds_dwordx4 v254, s[98:99]
	ds_read_b64_tr_b16 v[88:89], v207 offset:30720
	ds_read_b64_tr_b16 v[90:91], v207 offset:31232
	s_waitcnt lgkmcnt(6)
	v_mfma_f32_32x32x16_bf16 v[68:83], v[156:159], v[84:87], v[68:83]
	v_exp_f32_e32 v136, v136
	v_exp_f32_e32 v137, v137
	ds_read_b64_tr_b16 v[84:85], v207 offset:27648
	ds_read_b64_tr_b16 v[86:87], v207 offset:28160
	s_waitcnt lgkmcnt(6)
	v_mfma_f32_32x32x16_bf16 v[52:67], v[156:159], v[4:7], v[52:67]
	v_exp_f32_e32 v138, v138
	v_exp_f32_e32 v139, v139
	ds_read_b64_tr_b16 v[4:5], v207 offset:31744
	ds_read_b64_tr_b16 v[6:7], v207 offset:32256
	s_waitcnt lgkmcnt(6)
	v_mfma_f32_32x32x16_bf16 v[68:83], v[152:155], v[14:17], v[68:83]
	v_exp_f32_e32 v140, v140
	v_exp_f32_e32 v141, v141
	s_lshl_b32 m0, s60, 14
	s_add_i32 m0, m0, s58
	s_add_u32 s98, s100, s30
	s_addc_u32 s99, s101, s31
	global_load_lds_dwordx4 v255, s[98:99]
	ds_read_b64_tr_b16 v[14:15], v207 offset:32768
	ds_read_b64_tr_b16 v[16:17], v207 offset:33280
	s_waitcnt lgkmcnt(6)
	v_mfma_f32_32x32x16_bf16 v[52:67], v[152:155], v[88:91], v[52:67]
	v_exp_f32_e32 v142, v142
	v_exp_f32_e32 v143, v143
	ds_read_b64_tr_b16 v[88:89], v207 offset:36864
	ds_read_b64_tr_b16 v[90:91], v207 offset:37376
	s_waitcnt lgkmcnt(6)
	v_mfma_f32_32x32x16_bf16 v[68:83], v[148:151], v[84:87], v[68:83]
	v_exp_f32_e32 v144, v144
	v_exp_f32_e32 v145, v145
	ds_read_b64_tr_b16 v[84:85], v207 offset:33792
	ds_read_b64_tr_b16 v[86:87], v207 offset:34304
	s_waitcnt lgkmcnt(6)
	v_mfma_f32_32x32x16_bf16 v[52:67], v[148:151], v[4:7], v[52:67]
	v_exp_f32_e32 v146, v146
	v_exp_f32_e32 v147, v147
	ds_read_b64_tr_b16 v[92:93], v207 offset:37888
	ds_read_b64_tr_b16 v[94:95], v207 offset:38400
	s_lshl_b32 s11, s60, 13
	v_add_u32_e32 v4, s11, v222
	ds_read_b128 v[96:99], v4
	ds_read_b128 v[164:167], v4 offset:512
	s_waitcnt lgkmcnt(8)
	v_mfma_f32_32x32x16_bf16 v[36:51], v[160:163], v[14:17], v[36:51]
	v_exp_f32_e32 v116, v116
	v_exp_f32_e32 v117, v117
	ds_read_b64_tr_b16 v[14:15], v207 offset:34816
	ds_read_b64_tr_b16 v[16:17], v207 offset:35328
	ds_read_b128 v[168:171], v4 offset:2048
	ds_read_b128 v[172:175], v4 offset:2560
	s_waitcnt lgkmcnt(10)
	v_mfma_f32_32x32x16_bf16 v[20:35], v[160:163], v[88:91], v[20:35]
	v_exp_f32_e32 v118, v118
	v_exp_f32_e32 v119, v119
	ds_read_b64_tr_b16 v[88:89], v207 offset:38912
	ds_read_b64_tr_b16 v[90:91], v207 offset:39424
	ds_read_b128 v[176:179], v4 offset:4096
	ds_read_b128 v[180:183], v4 offset:4608
	s_waitcnt lgkmcnt(12)
	v_mfma_f32_32x32x16_bf16 v[36:51], v[156:159], v[84:87], v[36:51]
	v_exp_f32_e32 v120, v120
	v_exp_f32_e32 v121, v121
	ds_read_b64_tr_b16 v[84:85], v207 offset:35840
	ds_read_b64_tr_b16 v[86:87], v207 offset:36352
	ds_read_b128 v[184:187], v4 offset:6144
	ds_read_b128 v[4:7], v4 offset:6656
	s_waitcnt lgkmcnt(14)
	v_mfma_f32_32x32x16_bf16 v[20:35], v[156:159], v[92:95], v[20:35]
	v_exp_f32_e32 v122, v122
	v_exp_f32_e32 v123, v123
	ds_read_b64_tr_b16 v[92:93], v207 offset:39936
	ds_read_b64_tr_b16 v[94:95], v207 offset:40448
	s_waitcnt lgkmcnt(12)
	v_mfma_f32_32x32x16_bf16 v[36:51], v[152:155], v[14:17], v[36:51]
	v_exp_f32_e32 v124, v124
	v_exp_f32_e32 v125, v125
	ds_read_b128 v[14:17], v219
	s_waitcnt lgkmcnt(9)
	v_mfma_f32_32x32x16_bf16 v[20:35], v[152:155], v[88:91], v[20:35]
	v_exp_f32_e32 v126, v126
	v_exp_f32_e32 v127, v127
	s_addk_i32 m0, 0x2000
	s_add_u32 s98, s100, s34
	s_addc_u32 s99, s101, s35
	global_load_lds_dwordx4 v255, s[98:99]
	s_waitcnt lgkmcnt(5)
	v_mfma_f32_32x32x16_bf16 v[36:51], v[148:151], v[84:87], v[36:51]
	v_exp_f32_e32 v128, v128
	v_exp_f32_e32 v129, v129
	s_waitcnt lgkmcnt(1)
	v_mfma_f32_32x32x16_bf16 v[20:35], v[148:151], v[92:95], v[20:35]
	v_exp_f32_e32 v130, v130
	v_exp_f32_e32 v131, v131
	s_waitcnt vmcnt(3) lgkmcnt(0)
	s_barrier
; #define TWAIT_BAR(N) asm volatile("s_waitcnt vmcnt(" #N ") lgkmcnt(0)\n\ts_barrier" ::: "memory")
; #define RESC() do { if constexpr (!NOMAX) if (resc) { asm volatile("s_waitcnt lgkmcnt(0)" ::: "memory"); \
;         _Pragma("unroll") for (int d_ = 0; d_ < 2; ++d_) _Pragma("unroll") for (int r = 0; r < 16; ++r) o[d_][r] *= wsf[crow(r, hi)]; } } while (0)
; #define ROT() do { sl_prev = sl_cur; sl_cur = sl_next; sl_next = (sl_next == 2 * SLOTB) ? 0 : sl_next + SLOTB; } while (0)
; #define RESC() do { if constexpr (!NOMAX) if (resc) { asm volatile("s_waitcnt lgkmcnt(0)" ::: "memory"); \
;         _Pragma("unroll") for (int d_ = 0; d_ < 4; ++d_) _Pragma("unroll") for (int r = 0; r < 16; ++r) o[d_][r] *= wsf[crow(r, hi)]; } } while (0)
; #define ROT() do { sl_prev = sl_cur; sl_cur = sl_next; sl_next = (sl_next == 2) ? 0 : sl_next + 1; } while (0)
; #define RESC() do { if (resc) { asm volatile("s_waitcnt lgkmcnt(0)" ::: "memory"); \
;         _Pragma("unroll") for (int d_ = 0; d_ < 4; ++d_) _Pragma("unroll") for (int r = 0; r < 16; ++r) o[d_][r] *= wsf[crow(r, hi)]; } } while (0)
; template <bool NOMAX>
; __device__ __forceinline__ void diff_unit(const AttnCtx& C, int u, LAS unsigned char* lds) {
;     ...
;     int kk = 1;
;     for (; kk + 7 < n; kk += 2) {
;         STEP(pB0, pB1, pA0, pA1, kk, true, true, true, false);     TWAIT_BAR(3); RESC(); ROT();
;         STEP(pA0, pA1, pB0, pB1, kk + 1, true, true, true, false); TWAIT_BAR(3); RESC(); ROT();
	s_add_i32 s16, s60, 1
	s_cmp_lg_u32 s60, 2
	s_cselect_b32 s59, s16, 0
	ds_read_b128 v[188:191], v219 offset:1024
	v_lshl_add_u32 v207, s10, 14, v214
	s_waitcnt lgkmcnt(1)
	v_mfma_f32_32x32x16_bf16 v[100:115], v[96:99], v[14:17], 0
	v_add_f32_e32 v84, v132, v133
	v_add_f32_e32 v84, v134, v84
	v_add_f32_e32 v84, v135, v84
	v_add_f32_e32 v84, v136, v84
	v_add_f32_e32 v84, v137, v84
	v_cvt_pk_bf16_f32 v160, v132, v133
	v_cvt_pk_bf16_f32 v161, v134, v135
	s_nop 0
	v_add_f32_e32 v84, v138, v84
	v_add_f32_e32 v84, v139, v84
	v_add_f32_e32 v84, v140, v84
	v_add_f32_e32 v148, v141, v84
	v_mfma_f32_32x32x16_bf16 v[84:99], v[164:167], v[14:17], 0
	v_cvt_pk_bf16_f32 v162, v136, v137
	v_cvt_pk_bf16_f32 v163, v138, v139
	ds_read_b128 v[14:17], v219 offset:2048
	ds_read_b64_tr_b16 v[132:133], v207 offset:24576
	ds_read_b64_tr_b16 v[134:135], v207 offset:25088
	s_waitcnt lgkmcnt(3)
	v_mfma_f32_32x32x16_bf16 v[100:115], v[168:171], v[188:191], v[100:115]
	v_add_f32_e32 v136, v142, v148
	v_add_f32_e32 v136, v143, v136
	v_add_f32_e32 v136, v144, v136
	v_add_f32_e32 v136, v145, v136
	v_cvt_pk_bf16_f32 v156, v140, v141
	v_cvt_pk_bf16_f32 v157, v142, v143
	v_mfma_f32_32x32x16_bf16 v[84:99], v[172:175], v[188:191], v[84:99]
	v_add_f32_e32 v136, v146, v136
	v_add_f32_e32 v136, v147, v136
	v_add_f32_e32 v136, v116, v136
	v_add_f32_e32 v148, v117, v136
	v_cvt_pk_bf16_f32 v158, v144, v145
	v_cvt_pk_bf16_f32 v159, v146, v147
	ds_read_b128 v[136:139], v219 offset:3072
	ds_read_b64_tr_b16 v[140:141], v207 offset:28672
	ds_read_b64_tr_b16 v[142:143], v207 offset:29184
	s_waitcnt lgkmcnt(5)
	v_mfma_f32_32x32x16_bf16 v[100:115], v[176:179], v[14:17], v[100:115]
	v_add_f32_e32 v144, v118, v148
	v_add_f32_e32 v144, v119, v144
	v_add_f32_e32 v144, v120, v144
	v_add_f32_e32 v144, v121, v144
	v_cvt_pk_bf16_f32 v152, v116, v117
	v_cvt_pk_bf16_f32 v153, v118, v119
	v_mfma_f32_32x32x16_bf16 v[84:99], v[180:183], v[14:17], v[84:99]
	v_add_f32_e32 v14, v122, v144
	v_add_f32_e32 v14, v123, v14
	v_add_f32_e32 v14, v124, v14
	v_add_f32_e32 v116, v125, v14
	v_cvt_pk_bf16_f32 v154, v120, v121
	v_cvt_pk_bf16_f32 v155, v122, v123
	ds_read_b64_tr_b16 v[14:15], v207 offset:25600
	ds_read_b64_tr_b16 v[16:17], v207 offset:26112
	s_waitcnt lgkmcnt(4)
	v_mfma_f32_32x32x16_bf16 v[100:115], v[184:187], v[136:139], v[100:115]
	v_add_f32_e32 v116, v126, v116
	v_add_f32_e32 v116, v127, v116
	v_add_f32_e32 v116, v128, v116
	v_add_f32_e32 v116, v129, v116
	v_cvt_pk_bf16_f32 v148, v124, v125
	v_cvt_pk_bf16_f32 v149, v126, v127
	v_mfma_f32_32x32x16_bf16 v[84:99], v[4:7], v[136:139], v[84:99]
	v_add_f32_e32 v4, v130, v116
	v_add_f32_e32 v4, v131, v4
	v_cvt_pk_bf16_f32 v150, v128, v129
	v_cvt_pk_bf16_f32 v151, v130, v131
	v_add_f32_e32 v225, v2, v4
	ds_read_b64_tr_b16 v[4:5], v207 offset:29696
	ds_read_b64_tr_b16 v[6:7], v207 offset:30208
	v_mfma_f32_32x32x16_bf16 v[68:83], v[160:163], v[132:135], v[68:83]
	v_exp_f32_e32 v100, v100
	v_exp_f32_e32 v101, v101
	ds_read_b64_tr_b16 v[10:11], v207 offset:26624
	ds_read_b64_tr_b16 v[12:13], v207 offset:27136
	s_waitcnt lgkmcnt(6)
	v_mfma_f32_32x32x16_bf16 v[52:67], v[160:163], v[140:143], v[52:67]
	v_exp_f32_e32 v102, v102
	v_exp_f32_e32 v103, v103
	s_lshl_b32 m0, s60, 13
	s_add_i32 m0, m0, s49
	s_add_u32 s98, s100, s36
	s_addc_u32 s99, s101, s37
	global_load_lds_dwordx4 v254, s[98:99]
	ds_read_b64_tr_b16 v[116:117], v207 offset:30720
	ds_read_b64_tr_b16 v[118:119], v207 offset:31232
	s_waitcnt lgkmcnt(6)
	v_mfma_f32_32x32x16_bf16 v[68:83], v[156:159], v[14:17], v[68:83]
	v_exp_f32_e32 v104, v104
	v_exp_f32_e32 v105, v105
	ds_read_b64_tr_b16 v[14:15], v207 offset:27648
	ds_read_b64_tr_b16 v[16:17], v207 offset:28160
	s_waitcnt lgkmcnt(6)
	v_mfma_f32_32x32x16_bf16 v[52:67], v[156:159], v[4:7], v[52:67]
	v_exp_f32_e32 v106, v106
	v_exp_f32_e32 v107, v107
	ds_read_b64_tr_b16 v[4:5], v207 offset:31744
	ds_read_b64_tr_b16 v[6:7], v207 offset:32256
	s_waitcnt lgkmcnt(6)
	v_mfma_f32_32x32x16_bf16 v[68:83], v[152:155], v[10:13], v[68:83]
	v_exp_f32_e32 v108, v108
	v_exp_f32_e32 v109, v109
	s_lshl_b32 m0, s59, 14
	s_add_i32 m0, m0, s58
	s_add_u32 s98, s100, s38
	s_addc_u32 s99, s101, s39
	global_load_lds_dwordx4 v255, s[98:99]
	ds_read_b64_tr_b16 v[10:11], v207 offset:32768
	ds_read_b64_tr_b16 v[12:13], v207 offset:33280
	s_waitcnt lgkmcnt(6)
	v_mfma_f32_32x32x16_bf16 v[52:67], v[152:155], v[116:119], v[52:67]
	v_exp_f32_e32 v110, v110
	v_exp_f32_e32 v111, v111
	ds_read_b64_tr_b16 v[116:117], v207 offset:36864
	ds_read_b64_tr_b16 v[118:119], v207 offset:37376
	s_waitcnt lgkmcnt(6)
	v_mfma_f32_32x32x16_bf16 v[68:83], v[148:151], v[14:17], v[68:83]
	v_exp_f32_e32 v112, v112
	v_exp_f32_e32 v113, v113
	ds_read_b64_tr_b16 v[14:15], v207 offset:33792
	ds_read_b64_tr_b16 v[16:17], v207 offset:34304
	s_waitcnt lgkmcnt(6)
	v_mfma_f32_32x32x16_bf16 v[52:67], v[148:151], v[4:7], v[52:67]
	v_exp_f32_e32 v114, v114
	v_exp_f32_e32 v115, v115
	ds_read_b64_tr_b16 v[4:5], v207 offset:37888
	ds_read_b64_tr_b16 v[6:7], v207 offset:38400
	v_lshl_add_u32 v2, s59, 13, v222
	ds_read_b128 v[192:195], v2
	ds_read_b128 v[184:187], v2 offset:512
	s_waitcnt lgkmcnt(8)
	v_mfma_f32_32x32x16_bf16 v[36:51], v[160:163], v[10:13], v[36:51]
	v_exp_f32_e32 v84, v84
	v_exp_f32_e32 v85, v85
	ds_read_b64_tr_b16 v[10:11], v207 offset:34816
	ds_read_b64_tr_b16 v[12:13], v207 offset:35328
	ds_read_b128 v[188:191], v2 offset:2048
	ds_read_b128 v[180:183], v2 offset:2560
	s_waitcnt lgkmcnt(10)
	v_mfma_f32_32x32x16_bf16 v[20:35], v[160:163], v[116:119], v[20:35]
	v_exp_f32_e32 v86, v86
	v_exp_f32_e32 v87, v87
	ds_read_b64_tr_b16 v[120:121], v207 offset:38912
	ds_read_b64_tr_b16 v[122:123], v207 offset:39424
	ds_read_b128 v[176:179], v2 offset:4096
	ds_read_b128 v[172:175], v2 offset:4608
	s_waitcnt lgkmcnt(12)
	v_mfma_f32_32x32x16_bf16 v[36:51], v[156:159], v[14:17], v[36:51]
	v_exp_f32_e32 v88, v88
	v_exp_f32_e32 v89, v89
	ds_read_b64_tr_b16 v[14:15], v207 offset:35840
	ds_read_b64_tr_b16 v[16:17], v207 offset:36352
	ds_read_b128 v[168:171], v2 offset:6144
	ds_read_b128 v[164:167], v2 offset:6656
	s_waitcnt lgkmcnt(14)
	v_mfma_f32_32x32x16_bf16 v[20:35], v[156:159], v[4:7], v[20:35]
	v_exp_f32_e32 v90, v90
	v_exp_f32_e32 v91, v91
	ds_read_b64_tr_b16 v[4:5], v207 offset:39936
	ds_read_b64_tr_b16 v[6:7], v207 offset:40448
	s_waitcnt lgkmcnt(12)
	v_mfma_f32_32x32x16_bf16 v[36:51], v[152:155], v[10:13], v[36:51]
	v_exp_f32_e32 v92, v92
	v_exp_f32_e32 v93, v93
	ds_read_b128 v[116:119], v219
	s_waitcnt lgkmcnt(9)
	v_mfma_f32_32x32x16_bf16 v[20:35], v[152:155], v[120:123], v[20:35]
	v_exp_f32_e32 v94, v94
	v_exp_f32_e32 v95, v95
	s_addk_i32 m0, 0x2000
	s_add_u32 s98, s100, s40
	s_addc_u32 s99, s101, s41
	global_load_lds_dwordx4 v255, s[98:99]
	s_waitcnt lgkmcnt(5)
	v_mfma_f32_32x32x16_bf16 v[36:51], v[148:151], v[14:17], v[36:51]
	v_exp_f32_e32 v96, v96
	v_exp_f32_e32 v97, v97
	s_waitcnt lgkmcnt(1)
	v_mfma_f32_32x32x16_bf16 v[20:35], v[148:151], v[4:7], v[20:35]
	v_exp_f32_e32 v98, v98
	v_exp_f32_e32 v99, v99
	s_add_i32 s10, s59, 1
	s_cmp_lg_u32 s59, 2
	s_waitcnt vmcnt(3) lgkmcnt(0)
	s_barrier
; #define TWAIT_BAR(N) asm volatile("s_waitcnt vmcnt(" #N ") lgkmcnt(0)\n\ts_barrier" ::: "memory")
; #define RESC() do { if constexpr (!NOMAX) if (resc) { asm volatile("s_waitcnt lgkmcnt(0)" ::: "memory"); \
;         _Pragma("unroll") for (int d_ = 0; d_ < 2; ++d_) _Pragma("unroll") for (int r = 0; r < 16; ++r) o[d_][r] *= wsf[crow(r, hi)]; } } while (0)
; #define ROT() do { sl_prev = sl_cur; sl_cur = sl_next; sl_next = (sl_next == 2 * SLOTB) ? 0 : sl_next + SLOTB; } while (0)
; #define RESC() do { if constexpr (!NOMAX) if (resc) { asm volatile("s_waitcnt lgkmcnt(0)" ::: "memory"); \
;         _Pragma("unroll") for (int d_ = 0; d_ < 4; ++d_) _Pragma("unroll") for (int r = 0; r < 16; ++r) o[d_][r] *= wsf[crow(r, hi)]; } } while (0)
; #define ROT() do { sl_prev = sl_cur; sl_cur = sl_next; sl_next = (sl_next == 2) ? 0 : sl_next + 1; } while (0)
; #define RESC() do { if (resc) { asm volatile("s_waitcnt lgkmcnt(0)" ::: "memory"); \
;         _Pragma("unroll") for (int d_ = 0; d_ < 4; ++d_) _Pragma("unroll") for (int r = 0; r < 16; ++r) o[d_][r] *= wsf[crow(r, hi)]; } } while (0)
; template <bool NOMAX>
; __device__ __forceinline__ void diff_unit(const AttnCtx& C, int u, LAS unsigned char* lds) {
;     ...
;     for (; kk + 7 < n; kk += 2) {
;         STEP(pB0, pB1, pA0, pA1, kk, true, true, true, false);     TWAIT_BAR(3); RESC(); ROT();
;         STEP(pA0, pA1, pB0, pB1, kk + 1, true, true, true, false); TWAIT_BAR(3); RESC(); ROT();
;     }
	s_cselect_b32 s60, s10, 0
	s_add_i32 s16, s9, 2
	s_add_u32 s6, s6, 0x20000
	v_cmp_ge_u32_e32 vcc, s16, v226
	s_addc_u32 s7, s7, 0
	s_add_u32 s100, s100, 0x20000
	s_addc_u32 s101, s101, 0
	s_mov_b32 s11, s8
	s_cbranch_vccz .LBB0_463
	s_add_i32 s16, s9, -5
	s_branch .LBB0_467
